# diff-attention block A: exps shifted one MFMA gap earlier and bf16 packs moved into the QK MFMA shadows (QK chain starts sooner)
# baseline (speedup 1.0000x reference)
.LBB0_508:
.LBB0_509:
	s_add_i32 s20, s2, 0xffffc000
	s_and_b32 s20, s20, 0xc000
	v_add_u32_e32 v238, s20, v234
	s_add_i32 s20, s65, s20
	v_mfma_f32_32x32x16_bf16 v[0:15], v[160:163], v[128:131], v[0:15]
	ds_read_b64_tr_b16 v[196:197], v238
	ds_read_b64_tr_b16 v[198:199], v238 offset:512
	v_add_u32_e32 v96, s20, v228
	v_add_u32_e32 v97, s20, v229
	v_add_u32_e32 v98, s20, v230
	v_add_u32_e32 v99, s20, v231
	v_exp_f32_e32 v241, v80
	v_exp_f32_e32 v242, v81
	v_mfma_f32_32x32x16_bf16 v[0:15], v[164:167], v[132:135], v[0:15]
	ds_read_b64_tr_b16 v[192:193], v238 offset:1024
	ds_read_b64_tr_b16 v[194:195], v238 offset:1536
	s_add_i32 s22, s76, 4
	s_cmp_ge_u32 s22, s19
	s_cbranch_scc1 .LstgK_skip
	s_and_b64 s[38:39], s[16:17], exec
	s_cselect_b32 s22, s22, s3
	s_ashr_i32 s23, s22, 31
	s_lshl_b64 s[22:23], s[22:23], 16
	s_add_u32 s22, s74, s22
	s_addc_u32 s23, s75, s23
	s_add_i32 s38, s2, 0x8000
	s_and_b32 s38, s38, 0xc000
	s_add_i32 s38, s54, s38
	s_mov_b32 s39, m0
	s_mov_b32 m0, s38
	s_nop 0
	global_load_lds_dwordx4 v204, s[22:23]
	s_mov_b32 m0, s39
	s_add_u32 s22, s22, 0x80
	s_addc_u32 s23, s23, 0
	s_addk_i32 s38, 0x2000
	s_mov_b32 s39, m0
	s_mov_b32 m0, s38
	s_nop 0
	global_load_lds_dwordx4 v204, s[22:23]
	s_mov_b32 m0, s39
.LstgK_skip:
	v_exp_f32_e32 v243, v82
	v_exp_f32_e32 v244, v83
	v_exp_f32_e32 v245, v84
	v_exp_f32_e32 v246, v85
	v_mfma_f32_32x32x16_bf16 v[32:47], v[160:163], v[136:139], v[32:47]
	ds_read_b64_tr_b16 v[188:189], v238 offset:4096
	ds_read_b64_tr_b16 v[190:191], v238 offset:4608
	v_exp_f32_e32 v247, v86
	v_exp_f32_e32 v248, v87
	v_add_f32_e32 v100, v243, v241
	v_add_f32_e32 v101, v244, v242
	v_mfma_f32_32x32x16_bf16 v[32:47], v[164:167], v[140:143], v[32:47]
	ds_read_b64_tr_b16 v[184:185], v238 offset:5120
	ds_read_b64_tr_b16 v[186:187], v238 offset:5632
	s_cmp_ge_u32 s37, s18
	s_cbranch_scc1 .LstgV_skip
	s_add_i32 s22, s76, 3
	s_add_i32 s23, s3, 1
	s_and_b64 s[20:21], s[16:17], exec
	s_cselect_b32 s20, s22, s23
	s_ashr_i32 s21, s20, 31
	s_lshl_b64 s[20:21], s[20:21], 16
	s_add_u32 s20, s80, s20
	s_addc_u32 s21, s81, s21
	s_add_i32 s22, s2, 0x4000
	s_and_b32 s22, s22, 0xc000
	s_add_i32 s22, s22, 0
	s_add_i32 s22, s22, 0x10000
	s_add_i32 s23, s22, s55
	s_mov_b32 s38, m0
	s_mov_b32 m0, s23
	s_nop 0
	global_load_lds_dwordx4 v226, s[20:21]
	s_mov_b32 m0, s38
	s_add_i32 s22, s22, s57
	s_mov_b32 s23, m0
	s_mov_b32 m0, s22
	s_nop 0
	global_load_lds_dwordx4 v227, s[20:21]
	s_mov_b32 m0, s23
.LstgV_skip:
	v_exp_f32_e32 v249, v88
	v_exp_f32_e32 v250, v89
	v_add_f32_e32 v100, v245, v100
	v_add_f32_e32 v101, v246, v101
	v_mfma_f32_32x32x16_bf16 v[48:63], v[160:163], v[144:147], v[48:63]
	ds_read_b64_tr_b16 v[180:181], v238 offset:8192
	ds_read_b64_tr_b16 v[182:183], v238 offset:8704
	v_exp_f32_e32 v251, v90
	v_exp_f32_e32 v252, v91
	v_add_f32_e32 v100, v247, v100
	v_add_f32_e32 v101, v248, v101
	v_mfma_f32_32x32x16_bf16 v[48:63], v[164:167], v[148:151], v[48:63]
	ds_read_b64_tr_b16 v[176:177], v238 offset:9216
	ds_read_b64_tr_b16 v[178:179], v238 offset:9728
	ds_read_b128 v[128:131], v96 offset:4096
	v_exp_f32_e32 v253, v92
	v_exp_f32_e32 v239, v93
	v_add_f32_e32 v100, v249, v100
	v_add_f32_e32 v101, v250, v101
	v_mfma_f32_32x32x16_bf16 v[16:31], v[160:163], v[152:155], v[16:31]
	ds_read_b64_tr_b16 v[172:173], v238 offset:12288
	ds_read_b64_tr_b16 v[174:175], v238 offset:12800
	v_add_f32_e32 v100, v251, v100
	v_add_f32_e32 v101, v252, v101
	v_mfma_f32_32x32x16_bf16 v[16:31], v[164:167], v[156:159], v[16:31]
	ds_read_b64_tr_b16 v[168:169], v238 offset:13312
	ds_read_b64_tr_b16 v[170:171], v238 offset:13824
	ds_read_b128 v[132:135], v97 offset:4096
	ds_read_b128 v[136:139], v98 offset:4096
	ds_read_b128 v[140:143], v99 offset:4096
	v_exp_f32_e32 v240, v94
	v_exp_f32_e32 v99, v95
	v_add_f32_e32 v100, v253, v100
	v_add_f32_e32 v101, v239, v101
	v_add_f32_e32 v100, v240, v100
	v_add_f32_e32 v101, v99, v101
	v_add_f32_e32 v100, v100, v101
	v_add_f32_e32 v235, v235, v100
	v_cvt_pk_bf16_f32 v165, v240, v99
	s_waitcnt lgkmcnt(7)
	v_mfma_f32_32x32x16_bf16 v[96:111], v[128:131], v[112:115], v[64:79]
	v_max3_f32 v144, v80, v81, v82
	v_max3_f32 v145, v83, v84, v85
	v_cvt_pk_bf16_f32 v156, v241, v242
	v_cvt_pk_bf16_f32 v157, v243, v244
	s_waitcnt lgkmcnt(2)
	v_mfma_f32_32x32x16_bf16 v[96:111], v[132:135], v[116:119], v[96:111]
	v_max3_f32 v128, v144, v86, v87
	v_max3_f32 v129, v145, v88, v89
	v_cvt_pk_bf16_f32 v158, v245, v246
	v_cvt_pk_bf16_f32 v159, v247, v248
	s_waitcnt lgkmcnt(1)
	v_mfma_f32_32x32x16_bf16 v[96:111], v[136:139], v[120:123], v[96:111]
	v_max3_f32 v128, v128, v90, v91
	v_max3_f32 v129, v129, v92, v93
	s_nop 0
	v_max3_f32 v128, v128, v94, v95
	v_cvt_pk_bf16_f32 v162, v249, v250
	v_cvt_pk_bf16_f32 v163, v251, v252
	s_waitcnt lgkmcnt(0)
	v_mfma_f32_32x32x16_bf16 v[96:111], v[140:143], v[124:127], v[96:111]
	v_cvt_pk_bf16_f32 v164, v253, v239
	v_max_f32_e32 v128, v128, v129
	ds_bpermute_b32 v129, v214, v128
	s_andn2_b64 vcc, exec, s[0:1]
	s_cbranch_vccz .LBB0_522
